# differential-attention steady loop: -mhat carried in the C operand of the first QK MFMAs (registers freed by recomputing finishing-pass pointers), 32 v_sub per tile removed
# speedup vs baseline: 1.0480x; 1.0089x over previous
;   #define WB(a,b) do{ if constexpr(DV2){WAIT_BAR(b);} else {WAIT_BAR(a);} }while(0)
;   #define DMA_K(t,slot) glds16(ksrc+(long)TMAP(t)*KVBLK*PQ,(unsigned)__builtin_amdgcn_readfirstlane(kdst+(slot)))
;   #define DMA_V(t,slot) glds16(vsrc+(long)TMAP(t)*KVBLK*PQ,(unsigned)__builtin_amdgcn_readfirstlane(vdst+(slot)))
;   #define DMA_V2(t,slot) do{ if constexpr(DV2) glds16(v2src+(long)TMAP(t)*KVBLK*PQ,(unsigned)__builtin_amdgcn_readfirstlane(v2dst+(slot))); }while(0)
;     ...
;   int tid=threadIdx.x; asm volatile("":"+v"(tid)); const int lane=tid&63,r32=lane&31,hi=lane>>5; const int wid=__builtin_amdgcn_readfirstlane(tid>>6);
;   const bf16*Qw=Qu+(long)wid*QBLK*PQ;
;   const unsigned lds0=(unsigned)(uintptr_t)shm;
;   float*wsf=(float*)(shm+LDS_WS)+wid*64;
;   const bf16*ksrc=Kh+(long)lane*PQ+wid*8;
;   const bf16*vsrc=Vh+(long)(16*(wid&3)+(lane>>2))*PQ+(wid>>2)*32+(lane&3)*8;
;   const unsigned kdst=lds0+LDS_K+wid*1024, vdst=lds0+LDS_V+wid*1024;
;     ...
;   const bf16*v2src=DV2?V2h+(vsrc-Vh):vsrc; const unsigned v2dst=lds0+LDS_V2+wid*1024;
;     ...
;   const int vb0=(int)(lds0+LDS_V)+((lane>>4)&1)*32+(lane&3)*8+(4*hi+((lane&15)>>2))*64;
;   const char*Kbase=shm+LDS_K; bf16x8 kf[8];
;   const lds_cptr shm3=(lds_cptr)shm; const lds_cptr kp0=shm3+LDS_K+hi*1024+r32*16; const lds_cptr vp0=shm3+LDS_V+((lane>>4)&1)*32+(lane&3)*8+(4*hi+((lane&15)>>2))*64;
;   DMA_K(0,0);DMA_V(0,0);DMA_V2(0,0);DMA_K(1,SLOTB);
;   bf16x8 qr[4];
;   #pragma unroll
;   for(int d0=0;d0<4;++d0)qr[d0]=*reinterpret_cast<const bf16x8*>(&Qw[(long)r32*PQ+d0*16+hi*8]);
;   float mhat=0.f,l_reg=0.f;f32x16 o[ND];
;   #pragma unroll
;   for(int d_=0;d_<ND;++d_)o[d_]=f32x16{};
;   f32x16 negm=f32x16{}; if constexpr(!DV2) asm volatile("":"+v"(negm));
;   const f32x16 zero16=f32x16{};
;     ...
;   const int nq_r=qrow0+(wid>>1), nq_c=(wid&1)*32+r32, n_rsw=min(max(nq_r-4,0),56), n_cs=min(max(nq_c-8,0),48);
;     ...
;   bool resc=false;
;     ...
;   f32x16 pA0,pA1,pB0,pB1;
;   int sl_prev=0,sl_cur=0,sl_next=SLOTB;
;     ...
;   DMA_K(2,2*SLOTB);
;   WB(3,4);
;   qkt(pA0,pA1,Kbase,qr,NEGM,r32,hi);asm volatile("s_nop 15\n\ts_nop 7":"+v"(pA0),"+v"(pA1));CMASK(pA0,pA1,0);
.LBB0_258:
	s_or_b32 s13, s42, s40
	s_mul_i32 s6, s13, 0x1100
	s_mul_hi_u32 s7, s13, 0x1100
	s_add_u32 s6, s6, s38
	s_addc_u32 s7, s7, 0
	s_lshl_b64 s[6:7], s[6:7], 7
	v_readlane_b32 s44, v254, 25
	v_readlane_b32 s45, v254, 26
	s_add_u32 s16, s44, s6
	v_readlane_b32 s46, v254, 27
	s_addc_u32 s17, s45, s7
	s_mul_hi_u32 s6, s13, 0x88000
	s_mul_i32 s13, s13, 0x88000
	v_mov_b32_e32 v14, v234
	v_readlane_b32 s47, v254, 28
	s_add_u32 s14, s46, s13
	s_addc_u32 s15, s47, s6
	v_readfirstlane_b32 s13, v14
	s_ashr_i32 s30, s13, 6
	s_ashr_i32 s31, s30, 31
	v_and_b32_e32 v243, 63, v14
	s_lshl_b64 s[6:7], s[30:31], 12
	s_add_u32 s16, s16, s6
	v_lshlrev_b32_e32 v0, 7, v243
	s_addc_u32 s17, s17, s7
	v_lshl_add_u64 v[2:3], s[14:15], 0, v[0:1]
	s_lshl_b32 s14, s30, 3
	s_lshl_b32 s7, s30, 4
	v_bfe_u32 v0, v14, 2, 4
	s_ashr_i32 s15, s14, 31
	v_and_or_b32 v0, s7, 48, v0
	s_ashr_i32 s7, s13, 3
	v_lshl_add_u64 v[224:225], s[14:15], 1, v[2:3]
	s_and_b32 s14, s7, 0xffffffe0
	s_ashr_i32 s15, s14, 31
	s_and_b32 s6, s13, 0x3fffffc0
	v_lshlrev_b32_e32 v0, 7, v0
	s_lshl_b64 s[14:15], s[14:15], 1
	v_lshlrev_b32_e32 v4, 3, v14
	s_lshl_b32 s43, s30, 10
	v_lshl_add_u64 v[2:3], s[10:11], 0, v[0:1]
	v_and_b32_e32 v244, 24, v4
	s_cmp_lg_u32 0, -1
	v_lshl_add_u64 v[2:3], v[2:3], 0, s[14:15]
	v_lshlrev_b32_e32 v4, 1, v244
	v_mov_b32_e32 v5, v1
	s_cselect_b32 s7, 0, 0
	v_lshl_add_u64 v[226:227], v[2:3], 0, v[4:5]
	s_add_i32 s43, s43, s7
	v_lshl_add_u64 v[2:3], s[28:29], 0, v[0:1]
	s_mov_b32 s7, m0
	s_mov_b32 m0, s43
	s_nop 0
	global_load_lds_dwordx4 v[224:225], off
	s_mov_b32 m0, s7
	v_and_b32_e32 v211, 31, v14
	s_add_i32 s44, s43, 0x6000
	v_lshl_add_u64 v[2:3], v[2:3], 0, s[14:15]
	s_mov_b32 s7, m0
	s_mov_b32 m0, s44
	s_nop 0
	global_load_lds_dwordx4 v[226:227], off
	s_mov_b32 m0, s7
	v_bfe_u32 v242, v14, 5, 1
	v_lshl_add_u64 v[228:229], v[2:3], 0, v[4:5]
	s_add_i32 s45, s43, 0x14800
	s_mov_b32 s7, m0
	s_mov_b32 m0, s45
	s_nop 0
	global_load_lds_dwordx4 v[228:229], off
	s_mov_b32 m0, s7
	v_lshlrev_b32_e32 v0, 7, v211
	v_lshl_add_u64 v[2:3], v[224:225], 0, s[86:87]
	s_add_i32 s7, s43, 0x2000
	s_mov_b32 s13, m0
	s_mov_b32 m0, s7
	s_nop 0
	global_load_lds_dwordx4 v[2:3], off
	s_mov_b32 m0, s13
	v_lshl_or_b32 v0, v242, 4, v0
	global_load_dwordx4 v[162:165], v0, s[16:17]
	global_load_dwordx4 v[158:161], v0, s[16:17] offset:32
	global_load_dwordx4 v[154:157], v0, s[16:17] offset:64
	global_load_dwordx4 v[146:149], v0, s[16:17] offset:96
	v_lshlrev_b32_e32 v0, 10, v242
	v_lshlrev_b32_e32 v2, 4, v211
	v_add3_u32 v250, 0, v0, v2
	v_lshl_add_u64 v[2:3], v[224:225], 0, s[96:97]
	s_add_i32 s7, s43, 0x4000
	s_mov_b32 s13, m0
	s_mov_b32 m0, s7
	s_nop 0
	global_load_lds_dwordx4 v[2:3], off
	s_mov_b32 m0, s13
	s_waitcnt vmcnt(4) lgkmcnt(0)
	s_barrier
	ds_read_b128 v[2:5], v250
	ds_read_b128 v[6:9], v250 offset:512
	v_lshlrev_b32_e32 v0, 1, v14
	v_and_b32_e32 v247, 32, v0
	s_lshl_b32 s6, s6, 2
	s_add_i32 s33, s6, 0
	s_mov_b32 s82, 1
	s_movk_i32 s47, 0x2000
	s_movk_i32 s46, 0x4000
	s_andn2_b64 vcc, exec, s[4:5]
	v_lshlrev_b32_e32 v252, 4, v242
	v_lshl_add_u32 v245, v211, 2, s33
	v_readlane_b32 s48, v254, 29
	v_readlane_b32 s49, v254, 30
	v_readlane_b32 s50, v254, 31
	v_readlane_b32 s51, v254, 32
	v_readlane_b32 s52, v254, 33
	v_readlane_b32 s53, v254, 34
	v_readlane_b32 s54, v254, 35
	v_readlane_b32 s55, v254, 36
	v_readlane_b32 s56, v254, 37
	v_readlane_b32 s57, v254, 38
	v_readlane_b32 s58, v254, 39
	v_readlane_b32 s59, v254, 40
	s_waitcnt vmcnt(3) lgkmcnt(1)
	v_mfma_f32_32x32x16_bf16 v[34:49], v[2:5], v[162:165], 0
	s_waitcnt lgkmcnt(0)
	v_mfma_f32_32x32x16_bf16 v[18:33], v[6:9], v[162:165], 0
	ds_read_b128 v[2:5], v250 offset:2048
	ds_read_b128 v[6:9], v250 offset:2560
	s_waitcnt vmcnt(2) lgkmcnt(1)
	v_mfma_f32_32x32x16_bf16 v[34:49], v[2:5], v[158:161], v[34:49]
	ds_read_b128 v[2:5], v250 offset:4096
	s_waitcnt lgkmcnt(1)
	v_mfma_f32_32x32x16_bf16 v[18:33], v[6:9], v[158:161], v[18:33]
	ds_read_b128 v[6:9], v250 offset:4608
	s_waitcnt vmcnt(1) lgkmcnt(1)
	v_mfma_f32_32x32x16_bf16 v[34:49], v[2:5], v[154:157], v[34:49]
	ds_read_b128 v[2:5], v250 offset:6656
	ds_read_b128 v[10:13], v250 offset:6144
	s_waitcnt lgkmcnt(2)
	v_mfma_f32_32x32x16_bf16 v[18:33], v[6:9], v[154:157], v[18:33]
	v_lshlrev_b32_e32 v6, 4, v14
	v_and_b32_e32 v0, 0xc0, v6
	v_lshl_or_b32 v246, v242, 8, v0
	v_add_u32_e32 v0, 0, v247
	v_add3_u32 v251, v0, v244, v246
	v_add_u32_e32 v249, 0x6000, v251
	s_waitcnt vmcnt(0) lgkmcnt(0)
	v_mfma_f32_32x32x16_bf16 v[34:49], v[10:13], v[146:149], v[34:49]
	v_mfma_f32_32x32x16_bf16 v[18:33], v[2:5], v[146:149], v[18:33]
	s_nop 15
	s_nop 7
	s_waitcnt vmcnt(0) lgkmcnt(0)
	s_barrier
; #define WAIT_BAR(N) asm volatile("s_waitcnt vmcnt(" #N ") lgkmcnt(0)\n\ts_barrier":::"memory")
;   #define WB(a,b) do{ if constexpr(DV2){WAIT_BAR(b);} else {WAIT_BAR(a);} }while(0)
;   #define DMA_K(t,slot) glds16(ksrc+(long)TMAP(t)*KVBLK*PQ,(unsigned)__builtin_amdgcn_readfirstlane(kdst+(slot)))
;   #define DMA_V(t,slot) glds16(vsrc+(long)TMAP(t)*KVBLK*PQ,(unsigned)__builtin_amdgcn_readfirstlane(vdst+(slot)))
;   #define DMA_V2(t,slot) do{ if constexpr(DV2) glds16(v2src+(long)TMAP(t)*KVBLK*PQ,(unsigned)__builtin_amdgcn_readfirstlane(v2dst+(slot))); }while(0)
;   #define ROT() do{sl_prev=sl_cur;sl_cur=sl_next;sl_next=(sl_next==(NSLOT-1)*SLOTB)?0:sl_next+SLOTB;}while(0)
;     ...
;   float mhat=0.f,l_reg=0.f;f32x16 o[ND];
;   #pragma unroll
;   for(int d_=0;d_<ND;++d_)o[d_]=f32x16{};
;   f32x16 negm=f32x16{}; if constexpr(!DV2) asm volatile("":"+v"(negm));
;   const f32x16 zero16=f32x16{};
;     ...
;   qkt(pA0,pA1,Kbase,qr,NEGM,r32,hi);asm volatile("s_nop 15\n\ts_nop 7":"+v"(pA0),"+v"(pA1));CMASK(pA0,pA1,0);
;   START(pA0,pA1);
;   _Pragma("unroll") for(int r=0;r<16;++r)pA1[r]=__builtin_amdgcn_exp2f(pA1[r]);
;   WAIT_BAR(0);
;   DMA_K(3,0);DMA_V(1,SLOTB);DMA_V2(1,SLOTB);
;   ROT();
;   kload8(kf,kp0+sl_cur);
;   WB(2,3);
	s_nop 0
	v_max3_f32 v2, v34, v35, v18
	v_max3_f32 v3, v36, v37, v19
	s_nop 0
	v_max3_f32 v2, v2, v20, v21
	v_max3_f32 v3, v3, v40, v41
	s_nop 0
	v_max3_f32 v2, v2, v38, v39
	v_max3_f32 v3, v3, v24, v25
	s_nop 0
	v_max3_f32 v2, v2, v22, v23
	v_max3_f32 v3, v3, v44, v45
	s_nop 0
	v_max3_f32 v2, v2, v42, v43
	v_max3_f32 v3, v3, v28, v29
	s_nop 0
	v_max3_f32 v2, v2, v26, v27
	v_max3_f32 v3, v3, v48, v49
	s_nop 0
	v_max3_f32 v2, v2, v46, v47
	v_max3_f32 v3, v3, v32, v33
	s_nop 0
	v_max3_f32 v2, v2, v30, v31
	s_nop 0
	v_max_f32_e32 v2, v2, v3
	s_nop 0
	v_mov_b32_e32 v3, v2
	s_nop 1
	v_permlane32_swap_b32_e32 v2, v3
	v_max_f32_e32 v2, v2, v3
	s_nop 0
	v_add_f32_e32 v248, v1, v2
	v_sub_f32_e32 v3, v34, v2
	v_sub_f32_e32 v4, v18, v2
	v_sub_f32_e32 v5, v35, v2
	v_sub_f32_e32 v6, v19, v2
	v_sub_f32_e32 v7, v36, v2
	v_sub_f32_e32 v8, v20, v2
	v_sub_f32_e32 v9, v37, v2
	v_sub_f32_e32 v10, v21, v2
	v_sub_f32_e32 v11, v38, v2
	v_sub_f32_e32 v12, v22, v2
	v_sub_f32_e32 v13, v39, v2
	v_sub_f32_e32 v14, v23, v2
	v_sub_f32_e32 v15, v40, v2
	v_sub_f32_e32 v18, v24, v2
	v_sub_f32_e32 v19, v41, v2
	v_sub_f32_e32 v20, v25, v2
	v_sub_f32_e32 v21, v42, v2
	v_sub_f32_e32 v22, v26, v2
	v_sub_f32_e32 v23, v43, v2
	v_sub_f32_e32 v24, v27, v2
	v_sub_f32_e32 v25, v44, v2
	v_sub_f32_e32 v26, v28, v2
	v_sub_f32_e32 v27, v45, v2
	v_sub_f32_e32 v28, v29, v2
	v_sub_f32_e32 v29, v46, v2
	v_sub_f32_e32 v30, v30, v2
	v_sub_f32_e32 v34, v47, v2
	v_sub_f32_e32 v31, v31, v2
	v_sub_f32_e32 v35, v48, v2
	v_sub_f32_e32 v32, v32, v2
	v_sub_f32_e32 v36, v49, v2
	v_sub_f32_e32 v2, v33, v2
	s_nop 0
	v_exp_f32_e32 v98, v3
	v_exp_f32_e32 v97, v2
	v_lshl_add_u64 v[2:3], v[224:225], 0, s[0:1]
	s_mov_b32 s6, m0
	s_mov_b32 m0, s43
	s_nop 0
	global_load_lds_dwordx4 v[2:3], off
	s_mov_b32 m0, s6
	v_lshl_add_u64 v[2:3], v[226:227], 0, s[86:87]
	s_add_i32 s6, s43, 0x8000
	s_mov_b32 s7, m0
	s_mov_b32 m0, s6
	s_nop 0
	global_load_lds_dwordx4 v[2:3], off
	s_mov_b32 m0, s7
	v_lshl_add_u64 v[2:3], v[228:229], 0, s[86:87]
	s_add_i32 s6, s43, 0x16800
	s_mov_b32 s7, m0
	s_mov_b32 m0, s6
	s_nop 0
	global_load_lds_dwordx4 v[2:3], off
	s_mov_b32 m0, s7
	ds_read_b128 v[194:197], v250 offset:8192
	ds_read_b128 v[186:189], v250 offset:8704
	ds_read_b128 v[190:193], v250 offset:10240
	ds_read_b128 v[182:185], v250 offset:10752
	ds_read_b128 v[178:181], v250 offset:12288
	ds_read_b128 v[174:177], v250 offset:12800
	ds_read_b128 v[170:173], v250 offset:14336
	ds_read_b128 v[166:169], v250 offset:14848
	v_exp_f32_e32 v99, v5
	v_exp_f32_e32 v100, v7
	v_exp_f32_e32 v101, v9
	v_exp_f32_e32 v102, v11
	v_exp_f32_e32 v103, v13
	v_exp_f32_e32 v104, v15
	v_exp_f32_e32 v105, v19
	v_exp_f32_e32 v106, v21
	v_exp_f32_e32 v107, v23
	v_exp_f32_e32 v108, v25
	v_exp_f32_e32 v109, v27
	v_exp_f32_e32 v110, v29
	v_exp_f32_e32 v111, v34
	v_exp_f32_e32 v112, v35
	v_exp_f32_e32 v113, v36
	v_exp_f32_e32 v82, v4
	v_exp_f32_e32 v83, v6
	v_exp_f32_e32 v84, v8
	v_exp_f32_e32 v85, v10
	v_exp_f32_e32 v86, v12
	v_exp_f32_e32 v87, v14
	v_exp_f32_e32 v88, v18
	v_exp_f32_e32 v89, v20
	v_exp_f32_e32 v90, v22
	v_exp_f32_e32 v91, v24
	v_exp_f32_e32 v92, v26
	v_exp_f32_e32 v93, v28
	v_exp_f32_e32 v94, v30
	v_exp_f32_e32 v95, v31
	v_exp_f32_e32 v96, v32
	s_waitcnt vmcnt(3) lgkmcnt(0)
	s_barrier
	v_cmp_gt_u32_e64 s[6:7], 32, v243
	s_cbranch_vccnz .LBB0_274
	v_mov_b32_e32 v14, v1
	v_mov_b32_e32 v15, v1
	v_mov_b32_e32 v0, v1
	v_mov_b32_e32 v2, v1
	v_mov_b32_e32 v3, v1
	v_mov_b32_e32 v4, v1
	v_mov_b32_e32 v5, v1
	v_mov_b32_e32 v6, v1
	v_mov_b32_e32 v7, v1
	v_mov_b32_e32 v8, v1
	v_mov_b32_e32 v9, v1
	v_mov_b32_e32 v10, v1
	v_mov_b32_e32 v11, v1
	v_mov_b32_e32 v12, v1
	v_mov_b32_e32 v13, v1
	v_mov_b64_e32 v[80:81], v[14:15]
	v_mov_b64_e32 v[64:65], v[14:15]
	v_mov_b64_e32 v[48:49], v[14:15]
	v_mov_b64_e32 v[32:33], v[14:15]
	s_mov_b32 s22, 0
	s_movk_i32 s13, 0x4000
	s_movk_i32 s21, 0x2000
	v_mov_b32_e32 v232, 0
	s_mov_b32 s20, 6
	s_mov_b64 s[14:15], 0
	v_mov_b64_e32 v[78:79], v[12:13]
	v_mov_b64_e32 v[76:77], v[10:11]
	v_mov_b64_e32 v[74:75], v[8:9]
	v_mov_b64_e32 v[72:73], v[6:7]
	v_mov_b64_e32 v[70:71], v[4:5]
	v_mov_b64_e32 v[68:69], v[2:3]
	v_mov_b64_e32 v[66:67], v[0:1]
	v_mov_b64_e32 v[62:63], v[12:13]
	v_mov_b64_e32 v[60:61], v[10:11]
	v_mov_b64_e32 v[58:59], v[8:9]
	v_mov_b64_e32 v[56:57], v[6:7]
	v_mov_b64_e32 v[54:55], v[4:5]
	v_mov_b64_e32 v[52:53], v[2:3]
	v_mov_b64_e32 v[50:51], v[0:1]
	v_mov_b64_e32 v[46:47], v[12:13]
	v_mov_b64_e32 v[44:45], v[10:11]
	v_mov_b64_e32 v[42:43], v[8:9]
	v_mov_b64_e32 v[40:41], v[6:7]
	v_mov_b64_e32 v[38:39], v[4:5]
	v_mov_b64_e32 v[36:37], v[2:3]
	v_mov_b64_e32 v[34:35], v[0:1]
	v_mov_b64_e32 v[30:31], v[12:13]
	v_mov_b64_e32 v[28:29], v[10:11]
	v_mov_b64_e32 v[26:27], v[8:9]
	v_mov_b64_e32 v[24:25], v[6:7]
	v_mov_b64_e32 v[22:23], v[4:5]
	v_mov_b64_e32 v[20:21], v[2:3]
	v_mov_b64_e32 v[18:19], v[0:1]
	v_readfirstlane_b32 s48, v224
	v_readfirstlane_b32 s49, v225
	v_readfirstlane_b32 s50, v226
	v_readfirstlane_b32 s51, v227
	v_readfirstlane_b32 s52, v228
	v_readfirstlane_b32 s53, v229
	s_nop 1
	v_subrev_u32_e32 v202, s48, v224
	v_subrev_u32_e32 v203, s50, v226
	v_sub_f32_e32 v208, 0, v248
	v_sub_f32_e32 v209, 0, v248
	v_sub_f32_e32 v210, 0, v248
	v_sub_f32_e32 v211, 0, v248
	v_sub_f32_e32 v212, 0, v248
	v_sub_f32_e32 v213, 0, v248
	v_sub_f32_e32 v214, 0, v248
	v_sub_f32_e32 v215, 0, v248
	v_sub_f32_e32 v216, 0, v248
	v_sub_f32_e32 v217, 0, v248
	v_sub_f32_e32 v218, 0, v248
	v_sub_f32_e32 v219, 0, v248
	v_sub_f32_e32 v220, 0, v248
	v_sub_f32_e32 v221, 0, v248
	v_sub_f32_e32 v222, 0, v248
	v_sub_f32_e32 v223, 0, v248
.LBB0_260:
	v_add_u32_e32 v0, s22, v251
	ds_read_b64_tr_b16 v[198:199], v0 offset:24576
	ds_read_b64_tr_b16 v[200:201], v0 offset:25088
	s_waitcnt lgkmcnt(9)
	v_mfma_f32_32x32x16_bf16 v[130:145], v[194:197], v[162:165], v[208:223]
	v_add_f32_e32 v230, v98, v99
	v_cvt_pk_bf16_f32 v150, v98, v99
	v_add_f32_e32 v231, v100, v101
	v_cvt_pk_bf16_f32 v151, v100, v101
	v_add_f32_e32 v230, v102, v230
	v_add_f32_e32 v231, v103, v231
	ds_read_b64_tr_b16 v[194:195], v0 offset:28672
	ds_read_b64_tr_b16 v[196:197], v0 offset:29184
	s_waitcnt lgkmcnt(10)
	v_mfma_f32_32x32x16_bf16 v[114:129], v[186:189], v[162:165], v[208:223]
	v_add_f32_e32 v230, v104, v230
	v_cvt_pk_bf16_f32 v152, v102, v103
	v_add_f32_e32 v231, v105, v231
	v_cvt_pk_bf16_f32 v153, v104, v105
	v_add_f32_e32 v230, v106, v230
	v_add_f32_e32 v231, v107, v231
	ds_read_b64_tr_b16 v[102:103], v0 offset:25600
	ds_read_b64_tr_b16 v[104:105], v0 offset:26112
	s_waitcnt lgkmcnt(11)
	v_mfma_f32_32x32x16_bf16 v[130:145], v[190:193], v[158:161], v[130:145]
	v_add_f32_e32 v230, v108, v230
	v_cvt_pk_bf16_f32 v10, v106, v107
	v_add_f32_e32 v231, v109, v231
	v_cvt_pk_bf16_f32 v11, v108, v109
	v_add_f32_e32 v230, v110, v230
	v_add_f32_e32 v231, v111, v231
	ds_read_b64_tr_b16 v[98:99], v0 offset:29696
	ds_read_b64_tr_b16 v[100:101], v0 offset:30208
	s_waitcnt lgkmcnt(12)
	v_mfma_f32_32x32x16_bf16 v[114:129], v[182:185], v[158:161], v[114:129]
	v_add_f32_e32 v230, v112, v230
	v_cvt_pk_bf16_f32 v12, v110, v111
	v_add_f32_e32 v231, v113, v231
	v_cvt_pk_bf16_f32 v13, v112, v113
	v_add_f32_e32 v230, v82, v230
	v_add_f32_e32 v231, v83, v231
	ds_read_b64_tr_b16 v[110:111], v0 offset:26624
	ds_read_b64_tr_b16 v[112:113], v0 offset:27136
	s_waitcnt lgkmcnt(13)
	v_mfma_f32_32x32x16_bf16 v[130:145], v[178:181], v[154:157], v[130:145]
	v_add_f32_e32 v230, v84, v230
	v_cvt_pk_bf16_f32 v6, v82, v83
	v_add_f32_e32 v231, v85, v231
	v_cvt_pk_bf16_f32 v7, v84, v85
	v_add_f32_e32 v230, v86, v230
	v_add_f32_e32 v231, v87, v231
	ds_read_b64_tr_b16 v[106:107], v0 offset:30720
	ds_read_b64_tr_b16 v[108:109], v0 offset:31232
	s_waitcnt lgkmcnt(14)
	v_mfma_f32_32x32x16_bf16 v[114:129], v[174:177], v[154:157], v[114:129]
	v_add_f32_e32 v230, v88, v230
	v_cvt_pk_bf16_f32 v8, v86, v87
	v_add_f32_e32 v231, v89, v231
	v_cvt_pk_bf16_f32 v9, v88, v89
	v_add_f32_e32 v230, v90, v230
	v_add_f32_e32 v231, v91, v231
	ds_read_b64_tr_b16 v[86:87], v0 offset:27648
	ds_read_b64_tr_b16 v[88:89], v0 offset:28160
	s_waitcnt lgkmcnt(14)
	v_mfma_f32_32x32x16_bf16 v[130:145], v[170:173], v[146:149], v[130:145]
	v_add_f32_e32 v230, v92, v230
	v_cvt_pk_bf16_f32 v2, v90, v91
	v_add_f32_e32 v231, v93, v231
	v_cvt_pk_bf16_f32 v3, v92, v93
	v_add_f32_e32 v230, v94, v230
	v_add_f32_e32 v231, v95, v231
	ds_read_b64_tr_b16 v[82:83], v0 offset:31744
	ds_read_b64_tr_b16 v[84:85], v0 offset:32256
	v_mfma_f32_32x32x16_bf16 v[114:129], v[166:169], v[146:149], v[114:129]
	v_add_f32_e32 v230, v96, v230
	v_cvt_pk_bf16_f32 v4, v94, v95
	v_add_f32_e32 v231, v97, v231
	v_cvt_pk_bf16_f32 v5, v96, v97
	s_add_u32 s54, s48, s14
	s_addc_u32 s55, s49, s15
	s_add_u32 s56, s54, 0x8000
	s_addc_u32 s57, s55, 0
	s_add_i32 s16, s21, s43
	s_mov_b32 m0, s16
	s_nop 0
	global_load_lds_dwordx4 v202, s[56:57]
	s_add_u32 s56, s50, s14
	s_addc_u32 s57, s51, s15
	s_add_u32 s56, s56, 0x4000
	s_addc_u32 s57, s57, 0
	s_add_i32 s16, s13, s44
	s_mov_b32 m0, s16
	s_nop 0
	global_load_lds_dwordx4 v203, s[56:57]
	s_add_u32 s58, s52, s14
	s_addc_u32 s59, s53, s15
	s_add_u32 s58, s58, 0x4000
	s_addc_u32 s59, s59, 0
	s_add_i32 s16, s13, s45
	s_mov_b32 m0, s16
	s_nop 0
	global_load_lds_dwordx4 v203, s[58:59]
	v_add_f32_e32 v230, v230, v231
	v_add_f32_e32 v206, v232, v230
	v_max3_f32 v90, v130, v131, v132
	v_max3_f32 v90, v90, v133, v134
	v_max3_f32 v91, v114, v115, v116
	v_max3_f32 v90, v90, v135, v136
	v_max3_f32 v91, v91, v117, v118
	v_max3_f32 v90, v90, v137, v138
	v_max3_f32 v91, v91, v119, v120
	v_max3_f32 v90, v90, v139, v140
	v_max3_f32 v91, v91, v121, v122
	v_max3_f32 v90, v90, v141, v142
	v_max3_f32 v91, v91, v123, v124
	v_max3_f32 v90, v90, v143, v144
	v_max3_f32 v91, v91, v125, v126
	v_max3_f32 v91, v91, v127, v128
	v_max3_f32 v90, v90, v145, v129
	v_max_f32_e32 v0, v90, v91
	v_mov_b32_e32 v90, v0
	s_nop 1
	v_permlane32_swap_b32_e32 v0, v90
	v_max_f32_e32 v0, v0, v90
	v_cmp_lt_f32_e32 vcc, s84, v0
	s_cmp_lg_u64 vcc, 0
	s_cselect_b64 s[16:17], -1, 0
	s_cbranch_vccnz .LBB0_268
;   #define WB(a,b) do{ if constexpr(DV2){WAIT_BAR(b);} else {WAIT_BAR(a);} }while(0)
;   #define RESC() do{ if(resc){ asm volatile("s_waitcnt lgkmcnt(0)":::"memory"); \
;       _Pragma("unroll") for(int d_=0;d_<ND;++d_) _Pragma("unroll") for(int r=0;r<16;++r)o[d_][r]*=wsf[crow(r,hi)]; } }while(0)
;   #define ROT() do{sl_prev=sl_cur;sl_cur=sl_next;sl_next=(sl_next==(NSLOT-1)*SLOTB)?0:sl_next+SLOTB;}while(0)
;     ...
;   int t=1;
;   for(;t+5<NT;t+=2){
;     STEP(pB0,pB1,pA0,pA1,t,true,true,true);     WB(2,3); RESC(); ROT();
.LBB0_261:
	v_add_u32_e32 v0, s22, v249
	v_add_u32_e32 v166, 0xe800, v0
	s_waitcnt lgkmcnt(14)
	v_mfma_f32_32x32x16_bf16 v[66:81], v[150:153], v[198:201], v[66:81]
	v_exp_f32_e32 v130, v130
	v_exp_f32_e32 v131, v131
	ds_read_b64_tr_b16 v[90:91], v0 offset:59392
	ds_read_b64_tr_b16 v[92:93], v0 offset:59904
	s_waitcnt lgkmcnt(14)
	v_mfma_f32_32x32x16_bf16 v[50:65], v[150:153], v[194:197], v[50:65]
	v_exp_f32_e32 v132, v132
	v_exp_f32_e32 v133, v133
	ds_read_b64_tr_b16 v[94:95], v0 offset:63488
	ds_read_b64_tr_b16 v[96:97], v0 offset:64000
	s_waitcnt lgkmcnt(14)
	v_mfma_f32_32x32x16_bf16 v[66:81], v[10:13], v[102:105], v[66:81]
	v_exp_f32_e32 v134, v134
	v_exp_f32_e32 v135, v135
	ds_read_b64_tr_b16 v[102:103], v0 offset:60416
	ds_read_b64_tr_b16 v[104:105], v0 offset:60928
	s_waitcnt lgkmcnt(14)
	v_mfma_f32_32x32x16_bf16 v[50:65], v[10:13], v[98:101], v[50:65]
	v_exp_f32_e32 v136, v136
	v_exp_f32_e32 v137, v137
	ds_read_b64_tr_b16 v[98:99], v0 offset:64512
	ds_read_b64_tr_b16 v[100:101], v0 offset:65024
	s_waitcnt lgkmcnt(14)
	v_mfma_f32_32x32x16_bf16 v[66:81], v[6:9], v[110:113], v[66:81]
	v_exp_f32_e32 v138, v138
	v_exp_f32_e32 v139, v139
	ds_read_b64_tr_b16 v[110:111], v0 offset:61440
	ds_read_b64_tr_b16 v[112:113], v0 offset:61952
	s_waitcnt lgkmcnt(14)
	v_mfma_f32_32x32x16_bf16 v[50:65], v[6:9], v[106:109], v[50:65]
	v_exp_f32_e32 v140, v140
	v_exp_f32_e32 v141, v141
	ds_read_b64_tr_b16 v[106:107], v166 offset:6144
	ds_read_b64_tr_b16 v[108:109], v166 offset:6656
	s_waitcnt lgkmcnt(14)
	v_mfma_f32_32x32x16_bf16 v[66:81], v[2:5], v[86:89], v[66:81]
	v_exp_f32_e32 v142, v142
	v_exp_f32_e32 v143, v143
	ds_read_b64_tr_b16 v[190:191], v0 offset:62464
	ds_read_b64_tr_b16 v[192:193], v0 offset:62976
	s_waitcnt lgkmcnt(14)
	v_mfma_f32_32x32x16_bf16 v[50:65], v[2:5], v[82:85], v[50:65]
	v_exp_f32_e32 v144, v144
	v_exp_f32_e32 v145, v145
	ds_read_b64_tr_b16 v[194:195], v166 offset:7168
	ds_read_b64_tr_b16 v[196:197], v166 offset:7680
	s_waitcnt lgkmcnt(14)
	v_mfma_f32_32x32x16_bf16 v[34:49], v[150:153], v[90:93], v[34:49]
	v_exp_f32_e32 v114, v114
	v_exp_f32_e32 v115, v115
	s_waitcnt lgkmcnt(12)
	v_mfma_f32_32x32x16_bf16 v[18:33], v[150:153], v[94:97], v[18:33]
	v_exp_f32_e32 v116, v116
	v_exp_f32_e32 v117, v117
	v_add_u32_e32 v0, s13, v250
	ds_read_b128 v[86:89], v0
	ds_read_b128 v[82:85], v0 offset:512
	s_waitcnt lgkmcnt(12)
	v_mfma_f32_32x32x16_bf16 v[34:49], v[10:13], v[102:105], v[34:49]
	v_exp_f32_e32 v118, v118
	v_exp_f32_e32 v119, v119
	ds_read_b128 v[186:189], v0 offset:2048
	ds_read_b128 v[182:185], v0 offset:2560
	s_waitcnt lgkmcnt(12)
	v_mfma_f32_32x32x16_bf16 v[18:33], v[10:13], v[98:101], v[18:33]
	v_exp_f32_e32 v120, v120
	v_exp_f32_e32 v121, v121
	ds_read_b128 v[178:181], v0 offset:4096
	ds_read_b128 v[174:177], v0 offset:4608
	s_waitcnt lgkmcnt(12)
	v_mfma_f32_32x32x16_bf16 v[34:49], v[6:9], v[110:113], v[34:49]
	v_exp_f32_e32 v122, v122
	v_exp_f32_e32 v123, v123
	ds_read_b128 v[170:173], v0 offset:6144
	ds_read_b128 v[166:169], v0 offset:6656
	s_waitcnt lgkmcnt(12)
	v_mfma_f32_32x32x16_bf16 v[18:33], v[6:9], v[106:109], v[18:33]
	v_exp_f32_e32 v124, v124
	v_exp_f32_e32 v125, v125
	s_waitcnt lgkmcnt(10)
	v_mfma_f32_32x32x16_bf16 v[34:49], v[2:5], v[190:193], v[34:49]
	v_exp_f32_e32 v126, v126
	v_exp_f32_e32 v127, v127
	s_waitcnt lgkmcnt(8)
	v_mfma_f32_32x32x16_bf16 v[18:33], v[2:5], v[194:197], v[18:33]
	v_exp_f32_e32 v128, v128
	v_exp_f32_e32 v129, v129
	s_waitcnt vmcnt(3) lgkmcnt(0)
	s_barrier
	s_andn2_b64 vcc, exec, s[16:17]
	v_add_u32_e32 v0, s33, v252
	s_cbranch_vccnz .LBB0_263
	s_waitcnt lgkmcnt(0)
	ds_read_b128 v[90:93], v0 offset:49248
	ds_read_b128 v[94:97], v0 offset:49216
	ds_read_b128 v[98:101], v0 offset:49184
	ds_read_b128 v[102:105], v0 offset:49152
	s_waitcnt lgkmcnt(3)
	v_pk_mul_f32 v[78:79], v[78:79], v[90:91]
	s_waitcnt lgkmcnt(2)
	v_pk_mul_f32 v[74:75], v[74:75], v[94:95]
	s_waitcnt lgkmcnt(1)
	v_pk_mul_f32 v[70:71], v[70:71], v[98:99]
	v_pk_mul_f32 v[80:81], v[80:81], v[92:93]
	v_pk_mul_f32 v[76:77], v[76:77], v[96:97]
	v_pk_mul_f32 v[72:73], v[72:73], v[100:101]
	s_waitcnt lgkmcnt(0)
	v_pk_mul_f32 v[68:69], v[68:69], v[104:105]
	v_pk_mul_f32 v[66:67], v[66:67], v[102:103]
	v_pk_mul_f32 v[62:63], v[62:63], v[90:91]
	v_pk_mul_f32 v[58:59], v[58:59], v[94:95]
	v_pk_mul_f32 v[54:55], v[54:55], v[98:99]
	v_pk_mul_f32 v[64:65], v[64:65], v[92:93]
	v_pk_mul_f32 v[60:61], v[60:61], v[96:97]
	v_pk_mul_f32 v[56:57], v[56:57], v[100:101]
	v_pk_mul_f32 v[52:53], v[52:53], v[104:105]
	v_pk_mul_f32 v[50:51], v[50:51], v[102:103]
	v_pk_mul_f32 v[46:47], v[46:47], v[90:91]
	v_pk_mul_f32 v[42:43], v[42:43], v[94:95]
	v_pk_mul_f32 v[38:39], v[38:39], v[98:99]
	v_pk_mul_f32 v[48:49], v[48:49], v[92:93]
	v_pk_mul_f32 v[44:45], v[44:45], v[96:97]
	v_pk_mul_f32 v[40:41], v[40:41], v[100:101]
	v_pk_mul_f32 v[36:37], v[36:37], v[104:105]
	v_pk_mul_f32 v[34:35], v[34:35], v[102:103]
	v_pk_mul_f32 v[30:31], v[30:31], v[90:91]
	v_pk_mul_f32 v[26:27], v[26:27], v[94:95]
	v_pk_mul_f32 v[22:23], v[22:23], v[98:99]
	v_pk_mul_f32 v[32:33], v[32:33], v[92:93]
	v_pk_mul_f32 v[28:29], v[28:29], v[96:97]
	v_pk_mul_f32 v[24:25], v[24:25], v[100:101]
	v_pk_mul_f32 v[20:21], v[20:21], v[104:105]
	v_pk_mul_f32 v[18:19], v[18:19], v[102:103]
.LBB0_263:
	s_add_i32 s16, s13, 0x2000
	s_cmpk_lg_i32 s13, 0x4000
	s_cselect_b32 s47, s16, 0
	v_add_u32_e32 v207, s21, v251
	ds_read_b64_tr_b16 v[198:199], v207 offset:24576
	ds_read_b64_tr_b16 v[200:201], v207 offset:25088
	s_waitcnt lgkmcnt(9)
	v_mfma_f32_32x32x16_bf16 v[98:113], v[86:89], v[162:165], v[208:223]
	v_add_f32_e32 v230, v130, v131
	v_cvt_pk_bf16_f32 v150, v130, v131
	v_add_f32_e32 v231, v132, v133
	v_cvt_pk_bf16_f32 v151, v132, v133
	v_add_f32_e32 v230, v134, v230
	v_add_f32_e32 v231, v135, v231
	ds_read_b64_tr_b16 v[194:195], v207 offset:28672
	ds_read_b64_tr_b16 v[196:197], v207 offset:29184
	s_waitcnt lgkmcnt(10)
	v_mfma_f32_32x32x16_bf16 v[82:97], v[82:85], v[162:165], v[208:223]
	v_add_f32_e32 v230, v136, v230
	v_cvt_pk_bf16_f32 v152, v134, v135
	v_add_f32_e32 v231, v137, v231
	v_cvt_pk_bf16_f32 v153, v136, v137
	v_add_f32_e32 v230, v138, v230
	v_add_f32_e32 v231, v139, v231
	ds_read_b64_tr_b16 v[190:191], v207 offset:25600
	ds_read_b64_tr_b16 v[192:193], v207 offset:26112
	s_waitcnt lgkmcnt(11)
	v_mfma_f32_32x32x16_bf16 v[98:113], v[186:189], v[158:161], v[98:113]
	v_add_f32_e32 v230, v140, v230
	v_cvt_pk_bf16_f32 v10, v138, v139
	v_add_f32_e32 v231, v141, v231
	v_cvt_pk_bf16_f32 v11, v140, v141
	v_add_f32_e32 v230, v142, v230
	v_add_f32_e32 v231, v143, v231
	ds_read_b64_tr_b16 v[138:139], v207 offset:29696
	ds_read_b64_tr_b16 v[140:141], v207 offset:30208
	s_waitcnt lgkmcnt(12)
	v_mfma_f32_32x32x16_bf16 v[82:97], v[182:185], v[158:161], v[82:97]
	v_add_f32_e32 v230, v144, v230
	v_cvt_pk_bf16_f32 v12, v142, v143
	v_add_f32_e32 v231, v145, v231
	v_cvt_pk_bf16_f32 v13, v144, v145
	v_add_f32_e32 v230, v114, v230
	v_add_f32_e32 v231, v115, v231
	ds_read_b64_tr_b16 v[134:135], v207 offset:26624
	ds_read_b64_tr_b16 v[136:137], v207 offset:27136
	s_waitcnt lgkmcnt(13)
	v_mfma_f32_32x32x16_bf16 v[98:113], v[178:181], v[154:157], v[98:113]
	v_add_f32_e32 v230, v116, v230
	v_cvt_pk_bf16_f32 v6, v114, v115
	v_add_f32_e32 v231, v117, v231
	v_cvt_pk_bf16_f32 v7, v116, v117
	v_add_f32_e32 v230, v118, v230
	v_add_f32_e32 v231, v119, v231
	ds_read_b64_tr_b16 v[130:131], v207 offset:30720
	ds_read_b64_tr_b16 v[132:133], v207 offset:31232
	s_waitcnt lgkmcnt(14)
	v_mfma_f32_32x32x16_bf16 v[82:97], v[174:177], v[154:157], v[82:97]
	v_add_f32_e32 v230, v120, v230
	v_cvt_pk_bf16_f32 v8, v118, v119
	v_add_f32_e32 v231, v121, v231
	v_cvt_pk_bf16_f32 v9, v120, v121
	v_add_f32_e32 v230, v122, v230
	v_add_f32_e32 v231, v123, v231
	ds_read_b64_tr_b16 v[118:119], v207 offset:27648
	ds_read_b64_tr_b16 v[120:121], v207 offset:28160
	s_waitcnt lgkmcnt(14)
	v_mfma_f32_32x32x16_bf16 v[98:113], v[170:173], v[146:149], v[98:113]
	v_add_f32_e32 v230, v124, v230
	v_cvt_pk_bf16_f32 v2, v122, v123
	v_add_f32_e32 v231, v125, v231
	v_cvt_pk_bf16_f32 v3, v124, v125
	v_add_f32_e32 v230, v126, v230
	v_add_f32_e32 v231, v127, v231
	ds_read_b64_tr_b16 v[114:115], v207 offset:31744
	ds_read_b64_tr_b16 v[116:117], v207 offset:32256
	v_mfma_f32_32x32x16_bf16 v[82:97], v[166:169], v[146:149], v[82:97]
	v_add_f32_e32 v230, v128, v230
	v_cvt_pk_bf16_f32 v4, v126, v127
	v_add_f32_e32 v231, v129, v231
	v_cvt_pk_bf16_f32 v5, v128, v129
	s_add_u32 s56, s54, 0xa000
	s_addc_u32 s57, s55, 0
	s_add_i32 s16, s13, s43
	s_mov_b32 m0, s16
	s_nop 0
	global_load_lds_dwordx4 v202, s[56:57]
	s_add_u32 s56, s50, s14
	s_addc_u32 s57, s51, s15
	s_add_u32 s56, s56, 0x6000
	s_addc_u32 s57, s57, 0
	s_add_i32 s16, s47, s44
	s_mov_b32 m0, s16
	s_nop 0
	global_load_lds_dwordx4 v203, s[56:57]
	s_add_u32 s58, s52, s14
	s_addc_u32 s59, s53, s15
	s_add_u32 s58, s58, 0x6000
	s_addc_u32 s59, s59, 0
	s_add_i32 s16, s47, s45
	s_mov_b32 m0, s16
	s_nop 0
	global_load_lds_dwordx4 v203, s[58:59]
	v_max3_f32 v14, v98, v99, v100
	v_max3_f32 v14, v14, v101, v102
	v_max3_f32 v15, v82, v83, v84
	v_max3_f32 v14, v14, v103, v104
	v_max3_f32 v15, v15, v85, v86
	v_max3_f32 v14, v14, v105, v106
	v_max3_f32 v15, v15, v87, v88
	v_max3_f32 v14, v14, v107, v108
	v_max3_f32 v15, v15, v89, v90
	v_max3_f32 v14, v14, v109, v110
	v_max3_f32 v15, v15, v91, v92
	v_max3_f32 v14, v14, v111, v112
	v_max3_f32 v15, v15, v93, v94
	v_max3_f32 v15, v15, v95, v96
	v_max3_f32 v14, v14, v113, v97
	v_max_f32_e32 v14, v14, v15
	v_mov_b32_e32 v15, v14
	s_nop 1
	v_permlane32_swap_b32_e32 v14, v15
	v_max_f32_e32 v14, v14, v15
	v_cmp_lt_f32_e32 vcc, s84, v14
	s_cmp_lg_u64 vcc, 0
	v_add_f32_e32 v230, v230, v231
	v_add_f32_e32 v232, v206, v230
	s_cselect_b64 s[16:17], -1, 0
	s_cbranch_vccnz .LBB0_271
;   #define WB(a,b) do{ if constexpr(DV2){WAIT_BAR(b);} else {WAIT_BAR(a);} }while(0)
;   #define RESC() do{ if(resc){ asm volatile("s_waitcnt lgkmcnt(0)":::"memory"); \
;       _Pragma("unroll") for(int d_=0;d_<ND;++d_) _Pragma("unroll") for(int r=0;r<16;++r)o[d_][r]*=wsf[crow(r,hi)]; } }while(0)
;   #define ROT() do{sl_prev=sl_cur;sl_cur=sl_next;sl_next=(sl_next==(NSLOT-1)*SLOTB)?0:sl_next+SLOTB;}while(0)
;     ...
;   int t=1;
;   for(;t+5<NT;t+=2){
;     STEP(pB0,pB1,pA0,pA1,t,true,true,true);     WB(2,3); RESC(); ROT();
.LBB0_264:
	v_add_u32_e32 v14, s21, v249
	v_add_u32_e32 v15, 0xe800, v14
	s_waitcnt lgkmcnt(14)
	v_mfma_f32_32x32x16_bf16 v[66:81], v[150:153], v[198:201], v[66:81]
	v_exp_f32_e32 v98, v98
	v_exp_f32_e32 v99, v99
	ds_read_b64_tr_b16 v[122:123], v14 offset:59392
	ds_read_b64_tr_b16 v[124:125], v14 offset:59904
	s_waitcnt lgkmcnt(14)
	v_mfma_f32_32x32x16_bf16 v[50:65], v[150:153], v[194:197], v[50:65]
	v_exp_f32_e32 v100, v100
	v_exp_f32_e32 v101, v101
	ds_read_b64_tr_b16 v[126:127], v14 offset:63488
	ds_read_b64_tr_b16 v[128:129], v14 offset:64000
	s_waitcnt lgkmcnt(14)
	v_mfma_f32_32x32x16_bf16 v[66:81], v[10:13], v[190:193], v[66:81]
	v_exp_f32_e32 v102, v102
	v_exp_f32_e32 v103, v103
	ds_read_b64_tr_b16 v[142:143], v14 offset:60416
	ds_read_b64_tr_b16 v[144:145], v14 offset:60928
	s_waitcnt lgkmcnt(14)
	v_mfma_f32_32x32x16_bf16 v[50:65], v[10:13], v[138:141], v[50:65]
	v_exp_f32_e32 v104, v104
	v_exp_f32_e32 v105, v105
	ds_read_b64_tr_b16 v[138:139], v14 offset:64512
	ds_read_b64_tr_b16 v[140:141], v14 offset:65024
	s_waitcnt lgkmcnt(14)
	v_mfma_f32_32x32x16_bf16 v[66:81], v[6:9], v[134:137], v[66:81]
	v_exp_f32_e32 v106, v106
	v_exp_f32_e32 v107, v107
	ds_read_b64_tr_b16 v[134:135], v14 offset:61440
	ds_read_b64_tr_b16 v[136:137], v14 offset:61952
	s_waitcnt lgkmcnt(14)
	v_mfma_f32_32x32x16_bf16 v[50:65], v[6:9], v[130:133], v[50:65]
	v_exp_f32_e32 v108, v108
	v_exp_f32_e32 v109, v109
	ds_read_b64_tr_b16 v[130:131], v15 offset:6144
	ds_read_b64_tr_b16 v[132:133], v15 offset:6656
	s_waitcnt lgkmcnt(14)
	v_mfma_f32_32x32x16_bf16 v[66:81], v[2:5], v[118:121], v[66:81]
	v_exp_f32_e32 v110, v110
	v_exp_f32_e32 v111, v111
	ds_read_b64_tr_b16 v[118:119], v14 offset:62464
	ds_read_b64_tr_b16 v[120:121], v14 offset:62976
	s_waitcnt lgkmcnt(14)
	v_mfma_f32_32x32x16_bf16 v[50:65], v[2:5], v[114:117], v[50:65]
	v_exp_f32_e32 v112, v112
	v_exp_f32_e32 v113, v113
	ds_read_b64_tr_b16 v[114:115], v15 offset:7168
	ds_read_b64_tr_b16 v[116:117], v15 offset:7680
	s_waitcnt lgkmcnt(14)
	v_mfma_f32_32x32x16_bf16 v[34:49], v[150:153], v[122:125], v[34:49]
	v_exp_f32_e32 v82, v82
	v_exp_f32_e32 v83, v83
	s_waitcnt lgkmcnt(12)
	v_mfma_f32_32x32x16_bf16 v[18:33], v[150:153], v[126:129], v[18:33]
	v_exp_f32_e32 v84, v84
	v_exp_f32_e32 v85, v85
	v_add_u32_e32 v14, s47, v250
	ds_read_b128 v[194:197], v14
	ds_read_b128 v[186:189], v14 offset:512
	s_waitcnt lgkmcnt(12)
	v_mfma_f32_32x32x16_bf16 v[34:49], v[10:13], v[142:145], v[34:49]
	v_exp_f32_e32 v86, v86
	v_exp_f32_e32 v87, v87
	ds_read_b128 v[190:193], v14 offset:2048
	ds_read_b128 v[182:185], v14 offset:2560
	s_waitcnt lgkmcnt(12)
	v_mfma_f32_32x32x16_bf16 v[18:33], v[10:13], v[138:141], v[18:33]
	v_exp_f32_e32 v88, v88
	v_exp_f32_e32 v89, v89
	ds_read_b128 v[178:181], v14 offset:4096
	ds_read_b128 v[174:177], v14 offset:4608
	s_waitcnt lgkmcnt(12)
	v_mfma_f32_32x32x16_bf16 v[34:49], v[6:9], v[134:137], v[34:49]
	v_exp_f32_e32 v90, v90
	v_exp_f32_e32 v91, v91
	ds_read_b128 v[170:173], v14 offset:6144
	ds_read_b128 v[166:169], v14 offset:6656
	s_waitcnt lgkmcnt(12)
	v_mfma_f32_32x32x16_bf16 v[18:33], v[6:9], v[130:133], v[18:33]
	v_exp_f32_e32 v92, v92
	v_exp_f32_e32 v93, v93
	s_waitcnt lgkmcnt(10)
	v_mfma_f32_32x32x16_bf16 v[34:49], v[2:5], v[118:121], v[34:49]
	v_exp_f32_e32 v94, v94
	v_exp_f32_e32 v95, v95
	s_waitcnt lgkmcnt(8)
	v_mfma_f32_32x32x16_bf16 v[18:33], v[2:5], v[114:117], v[18:33]
	v_exp_f32_e32 v96, v96
	v_exp_f32_e32 v97, v97
	s_waitcnt vmcnt(3) lgkmcnt(0)
	s_barrier
	s_andn2_b64 vcc, exec, s[16:17]
	s_cbranch_vccnz .LBB0_266
	s_waitcnt lgkmcnt(0)
	ds_read_b128 v[114:117], v0 offset:49248
	ds_read_b128 v[118:121], v0 offset:49216
	ds_read_b128 v[122:125], v0 offset:49184
	ds_read_b128 v[126:129], v0 offset:49152
	s_waitcnt lgkmcnt(3)
	v_pk_mul_f32 v[78:79], v[78:79], v[114:115]
	s_waitcnt lgkmcnt(2)
	v_pk_mul_f32 v[74:75], v[74:75], v[118:119]
	s_waitcnt lgkmcnt(1)
	v_pk_mul_f32 v[70:71], v[70:71], v[122:123]
	v_pk_mul_f32 v[80:81], v[80:81], v[116:117]
	v_pk_mul_f32 v[76:77], v[76:77], v[120:121]
	v_pk_mul_f32 v[72:73], v[72:73], v[124:125]
	s_waitcnt lgkmcnt(0)
	v_pk_mul_f32 v[68:69], v[68:69], v[128:129]
	v_pk_mul_f32 v[66:67], v[66:67], v[126:127]
	v_pk_mul_f32 v[62:63], v[62:63], v[114:115]
	v_pk_mul_f32 v[58:59], v[58:59], v[118:119]
	v_pk_mul_f32 v[54:55], v[54:55], v[122:123]
	v_pk_mul_f32 v[64:65], v[64:65], v[116:117]
	v_pk_mul_f32 v[60:61], v[60:61], v[120:121]
	v_pk_mul_f32 v[56:57], v[56:57], v[124:125]
	v_pk_mul_f32 v[52:53], v[52:53], v[128:129]
	v_pk_mul_f32 v[50:51], v[50:51], v[126:127]
	v_pk_mul_f32 v[46:47], v[46:47], v[114:115]
	v_pk_mul_f32 v[42:43], v[42:43], v[118:119]
	v_pk_mul_f32 v[38:39], v[38:39], v[122:123]
	v_pk_mul_f32 v[48:49], v[48:49], v[116:117]
	v_pk_mul_f32 v[44:45], v[44:45], v[120:121]
	v_pk_mul_f32 v[40:41], v[40:41], v[124:125]
	v_pk_mul_f32 v[36:37], v[36:37], v[128:129]
	v_pk_mul_f32 v[34:35], v[34:35], v[126:127]
	v_pk_mul_f32 v[30:31], v[30:31], v[114:115]
	v_pk_mul_f32 v[26:27], v[26:27], v[118:119]
	v_pk_mul_f32 v[22:23], v[22:23], v[122:123]
	v_pk_mul_f32 v[32:33], v[32:33], v[116:117]
	v_pk_mul_f32 v[28:29], v[28:29], v[120:121]
	v_pk_mul_f32 v[24:25], v[24:25], v[124:125]
	v_pk_mul_f32 v[20:21], v[20:21], v[128:129]
	v_pk_mul_f32 v[18:19], v[18:19], v[126:127]

.LBB0_268:
	v_max_f32_e32 v0, v0, v0
	v_max_f32_e32 v90, 0, v0
	v_exp_f32_e64 v0, -v90
	s_and_saveexec_b64 s[18:19], s[6:7]
	ds_write_b32 v245, v0 offset:49152
	s_or_b64 exec, exec, s[18:19]
	v_add_f32_e32 v248, v248, v90
	v_mul_f32_e32 v206, v206, v0
	v_sub_f32_e32 v130, v130, v90
	v_sub_f32_e32 v131, v131, v90
	v_sub_f32_e32 v132, v132, v90
	v_sub_f32_e32 v133, v133, v90
	v_sub_f32_e32 v134, v134, v90
	v_sub_f32_e32 v135, v135, v90
	v_sub_f32_e32 v136, v136, v90
	v_sub_f32_e32 v137, v137, v90
	v_sub_f32_e32 v138, v138, v90
	v_sub_f32_e32 v139, v139, v90
	v_sub_f32_e32 v140, v140, v90
	v_sub_f32_e32 v141, v141, v90
	v_sub_f32_e32 v142, v142, v90
	v_sub_f32_e32 v143, v143, v90
	v_sub_f32_e32 v144, v144, v90
	v_sub_f32_e32 v145, v145, v90
	v_sub_f32_e32 v114, v114, v90
	v_sub_f32_e32 v115, v115, v90
	v_sub_f32_e32 v116, v116, v90
	v_sub_f32_e32 v117, v117, v90
	v_sub_f32_e32 v118, v118, v90
	v_sub_f32_e32 v119, v119, v90
	v_sub_f32_e32 v120, v120, v90
	v_sub_f32_e32 v121, v121, v90
	v_sub_f32_e32 v122, v122, v90
	v_sub_f32_e32 v123, v123, v90
	v_sub_f32_e32 v124, v124, v90
	v_sub_f32_e32 v125, v125, v90
	v_sub_f32_e32 v126, v126, v90
	v_sub_f32_e32 v127, v127, v90
	v_sub_f32_e32 v128, v128, v90
	v_sub_f32_e32 v129, v129, v90
	v_sub_f32_e32 v208, 0, v248
	v_sub_f32_e32 v209, 0, v248
	v_sub_f32_e32 v210, 0, v248
	v_sub_f32_e32 v211, 0, v248
	v_sub_f32_e32 v212, 0, v248
	v_sub_f32_e32 v213, 0, v248
	v_sub_f32_e32 v214, 0, v248
	v_sub_f32_e32 v215, 0, v248
	v_sub_f32_e32 v216, 0, v248
	v_sub_f32_e32 v217, 0, v248
	v_sub_f32_e32 v218, 0, v248
	v_sub_f32_e32 v219, 0, v248
	v_sub_f32_e32 v220, 0, v248
	v_sub_f32_e32 v221, 0, v248
	v_sub_f32_e32 v222, 0, v248
	v_sub_f32_e32 v223, 0, v248
	s_branch .LBB0_261
.LBB0_271:
	v_max_f32_e32 v14, v14, v14
	v_max_f32_e32 v15, 0, v14
	v_exp_f32_e64 v14, -v15
	s_and_saveexec_b64 s[18:19], s[6:7]
	ds_write_b32 v245, v14 offset:49152
	s_or_b64 exec, exec, s[18:19]
	v_add_f32_e32 v248, v248, v15
	v_mul_f32_e32 v232, v232, v14
	v_sub_f32_e32 v98, v98, v15
	v_sub_f32_e32 v99, v99, v15
	v_sub_f32_e32 v100, v100, v15
	v_sub_f32_e32 v101, v101, v15
	v_sub_f32_e32 v102, v102, v15
	v_sub_f32_e32 v103, v103, v15
	v_sub_f32_e32 v104, v104, v15
	v_sub_f32_e32 v105, v105, v15
	v_sub_f32_e32 v106, v106, v15
	v_sub_f32_e32 v107, v107, v15
	v_sub_f32_e32 v108, v108, v15
	v_sub_f32_e32 v109, v109, v15
	v_sub_f32_e32 v110, v110, v15
	v_sub_f32_e32 v111, v111, v15
	v_sub_f32_e32 v112, v112, v15
	v_sub_f32_e32 v113, v113, v15
	v_sub_f32_e32 v82, v82, v15
	v_sub_f32_e32 v83, v83, v15
	v_sub_f32_e32 v84, v84, v15
	v_sub_f32_e32 v85, v85, v15
	v_sub_f32_e32 v86, v86, v15
	v_sub_f32_e32 v87, v87, v15
	v_sub_f32_e32 v88, v88, v15
	v_sub_f32_e32 v89, v89, v15
	v_sub_f32_e32 v90, v90, v15
	v_sub_f32_e32 v91, v91, v15
	v_sub_f32_e32 v92, v92, v15
	v_sub_f32_e32 v93, v93, v15
	v_sub_f32_e32 v94, v94, v15
	v_sub_f32_e32 v95, v95, v15
	v_sub_f32_e32 v96, v96, v15
	v_sub_f32_e32 v97, v97, v15
	v_sub_f32_e32 v208, 0, v248
	v_sub_f32_e32 v209, 0, v248
	v_sub_f32_e32 v210, 0, v248
	v_sub_f32_e32 v211, 0, v248
	v_sub_f32_e32 v212, 0, v248
	v_sub_f32_e32 v213, 0, v248
	v_sub_f32_e32 v214, 0, v248
	v_sub_f32_e32 v215, 0, v248
	v_sub_f32_e32 v216, 0, v248
	v_sub_f32_e32 v217, 0, v248
	v_sub_f32_e32 v218, 0, v248
	v_sub_f32_e32 v219, 0, v248
	v_sub_f32_e32 v220, 0, v248
	v_sub_f32_e32 v221, 0, v248
	v_sub_f32_e32 v222, 0, v248
	v_sub_f32_e32 v223, 0, v248
	s_branch .LBB0_264

;   #define RESC() do{ if(resc){ asm volatile("s_waitcnt lgkmcnt(0)":::"memory"); \
;       _Pragma("unroll") for(int d_=0;d_<ND;++d_) _Pragma("unroll") for(int r=0;r<16;++r)o[d_][r]*=wsf[crow(r,hi)]; } }while(0)
;   #define ROT() do{sl_prev=sl_cur;sl_cur=sl_next;sl_next=(sl_next==(NSLOT-1)*SLOTB)?0:sl_next+SLOTB;}while(0)
;   #define ENDW(tt) do{ if((tt)+3<NT){WB(2,3);} else if((tt)+2<NT){WB(1,2);} else {WAIT_BAR(0);} }while(0)
;     ...
;   for(;t+1<NT;t+=2){
;     STEP(pB0,pB1,pA0,pA1,t,(t+3<NT),(t+1<NT),(t+1<NT));       ENDW(t);   RESC(); ROT();
;     STEP(pA0,pA1,pB0,pB1,t+1,(t+4<NT),(t+2<NT),(t+2<NT));     ENDW(t+1); RESC(); ROT();
;   }
.LBB0_281:
	v_and_b32_e32 v211, 31, v234
	s_add_i32 s82, s20, -3
	s_xor_b64 s[14:15], s[8:9], -1
	s_add_i32 s6, s82, 1
	s_cmp_ge_u32 s6, s39
	s_cbranch_scc1 .LBB0_275

; __device__ __forceinline__ void phase_attn(const Params& p, int l, unsigned char* smem) {
;     ...
;             __syncthreads();
;             const float g0 = p.subln_g[lane * 2], g1 = p.subln_g[lane * 2 + 1];
; #pragma unroll 8
;             for (int i = 0; i < 32; ++i) {
;                 const int qrow = w * 32 + i;
;                 const float2 a0 = *(const float2*)(blk + (size_t)qrow * 128 + lane * 2);
;                 const float2 a1 = *(const float2*)(blk + (size_t)(256 + qrow) * 128 + lane * 2);
;                 const unsigned zz = *(const unsigned*)(p.sz + (grow0 + qrow) * D + hh * 128 + lane * 2);
.LBB0_330:
	s_waitcnt vmcnt(63) expcnt(7) lgkmcnt(15)
	s_barrier
	v_ashrrev_i32_e32 v22, 1, v234
	v_and_b32_e32 v212, 0xffffffe0, v22
	v_ashrrev_i32_e32 v213, 31, v212
	v_lshlrev_b32_e32 v22, 3, v234
	v_and_b32_e32 v22, 0x1f8, v22
	v_mov_b32_e32 v23, 0
	v_readlane_b32 s14, v253, 40
	v_readlane_b32 s15, v253, 41
	v_readlane_b32 s16, v254, 31
	v_readlane_b32 s17, v254, 32
	v_readlane_b32 s18, v254, 33
	v_readlane_b32 s19, v254, 34
	v_readlane_b32 s20, v254, 44
	v_readlane_b32 s21, v254, 45
	v_and_b32_e32 v24, 63, v234
	v_lshl_add_u64 v[214:215], s[14:15], 0, v[22:23]
	v_lshlrev_b32_e32 v22, 2, v24
	v_lshlrev_b64 v[26:27], 9, v[212:213]
	v_lshl_add_u64 v[218:219], s[16:17], 0, v[22:23]
	v_lshl_add_u64 v[216:217], s[18:19], 0, v[22:23]
	v_lshlrev_b32_e32 v22, 3, v24
	v_add_u32_e32 v28, 0x100, v212
	v_or_b32_e32 v26, v26, v22
	v_ashrrev_i32_e32 v29, 31, v28
	v_lshl_add_u64 v[220:221], s[20:21], 0, v[26:27]
	v_lshlrev_b64 v[28:29], 9, v[28:29]
	v_or_b32_e32 v28, v28, v22
	v_lshl_add_u64 v[222:223], s[20:21], 0, v[28:29]
	global_load_dwordx2 v[2:3], v[214:215], off
	v_readlane_b32 s6, v254, 43
	s_or_b32 s6, s37, s6
	s_and_b64 s[4:5], s[4:5], exec
	v_readlane_b32 s4, v254, 42
	s_cselect_b32 s4, s6, s4
	s_mov_b32 s5, s83
	v_lshl_add_u64 v[4:5], v[212:213], 0, s[4:5]
	v_lshlrev_b64 v[6:7], 11, v[4:5]
	s_lshl_b32 s82, s36, 8
	v_lshl_add_u64 v[4:5], v[216:217], 0, v[6:7]
	v_lshl_add_u64 v[6:7], v[218:219], 0, v[6:7]
	s_mov_b64 s[4:5], 0
	s_movk_i32 s6, 0x2000
	s_mov_b32 s7, 0x800000
	s_movk_i32 s8, 0x1000
	s_movk_i32 s9, 0x3000
	s_mov_b64 s[10:11], 0x1000
	s_mov_b64 s[12:13], 0x8000
